# MFMA-shadow epilogue-load hoist: FFN1 SwiGLU epilogue ssq loads issued under the last K iteration's final MFMA block
# speedup vs baseline: 1.0094x; 1.0094x over previous
.LBB0_1916:
	s_add_u32 s2, s54, 0xfffc0080
	s_addc_u32 s3, s55, -1
	s_add_i32 vcc_lo, 0, 0x10000
	s_cmp_eq_u32 s81, 12
	s_cselect_b32 s3, s0, s3
	s_cselect_b32 s2, s1, s2
	v_add_u32_e32 v136, vcc_lo, v140
	s_cselect_b32 s83, s23, s80
	s_cselect_b32 s82, s25, s49
	s_add_i32 vcc_hi, 0, 0x14000
	ds_read_b128 v[132:135], v136
	ds_read_b128 v[144:147], v136 offset:1024
	ds_read_b128 v[148:151], v136 offset:2048
	ds_read_b128 v[152:155], v136 offset:3072
	v_add_u32_e32 v136, vcc_hi, v140
	ds_read_b128 v[156:159], v136
	ds_read_b128 v[160:163], v136 offset:1024
	ds_read_b128 v[164:167], v136 offset:2048
	ds_read_b128 v[168:171], v136 offset:3072
	v_lshl_add_u64 v[136:137], s[54:55], 0, v[130:131]
	s_add_i32 m0, s51, 0xc000
	ds_read_b128 v[172:175], v142
	ds_read_b128 v[176:179], v142 offset:1024
	ds_read_b128 v[180:183], v142 offset:2048
	ds_read_b128 v[200:203], v142 offset:3072
	ds_read_b128 v[204:207], v142 offset:4096
	ds_read_b128 v[208:211], v142 offset:5120
	ds_read_b128 v[212:215], v142 offset:6144
	ds_read_b128 v[216:219], v142 offset:7168
	global_load_lds_dwordx4 v[136:137], off
	v_lshl_add_u64 v[136:137], v[136:137], 0, s[84:85]
	s_add_i32 m0, s51, 0xe000
	s_nop 0
	global_load_lds_dwordx4 v[136:137], off
	s_waitcnt vmcnt(8)
	s_waitcnt lgkmcnt(0)
	s_barrier
	s_waitcnt lgkmcnt(0)
	v_mfma_f32_16x16x32_bf16 v[124:127], v[132:135], v[172:175], v[124:127]
	v_mfma_f32_16x16x32_bf16 v[120:123], v[148:151], v[172:175], v[120:123]
	v_mfma_f32_16x16x32_bf16 v[108:111], v[132:135], v[180:183], v[108:111]
	v_mfma_f32_16x16x32_bf16 v[104:107], v[148:151], v[180:183], v[104:107]
	v_mfma_f32_16x16x32_bf16 v[92:95], v[132:135], v[204:207], v[92:95]
	v_mfma_f32_16x16x32_bf16 v[88:91], v[148:151], v[204:207], v[88:91]
	v_mfma_f32_16x16x32_bf16 v[76:79], v[132:135], v[212:215], v[76:79]
	v_mfma_f32_16x16x32_bf16 v[72:75], v[148:151], v[212:215], v[72:75]
	v_mfma_f32_16x16x32_bf16 v[124:127], v[144:147], v[176:179], v[124:127]
	v_mfma_f32_16x16x32_bf16 v[120:123], v[152:155], v[176:179], v[120:123]
	v_mfma_f32_16x16x32_bf16 v[108:111], v[144:147], v[200:203], v[108:111]
	v_mfma_f32_16x16x32_bf16 v[104:107], v[152:155], v[200:203], v[104:107]
	v_mfma_f32_16x16x32_bf16 v[92:95], v[144:147], v[208:211], v[92:95]
	v_mfma_f32_16x16x32_bf16 v[88:91], v[152:155], v[208:211], v[88:91]
	v_mfma_f32_16x16x32_bf16 v[76:79], v[144:147], v[216:219], v[76:79]
	v_mfma_f32_16x16x32_bf16 v[72:75], v[152:155], v[216:219], v[72:75]
	v_mfma_f32_16x16x32_bf16 v[116:119], v[156:159], v[172:175], v[116:119]
	v_mfma_f32_16x16x32_bf16 v[112:115], v[164:167], v[172:175], v[112:115]
	v_mfma_f32_16x16x32_bf16 v[100:103], v[156:159], v[180:183], v[100:103]
	v_mfma_f32_16x16x32_bf16 v[96:99], v[164:167], v[180:183], v[96:99]
	v_mfma_f32_16x16x32_bf16 v[84:87], v[156:159], v[204:207], v[84:87]
	v_mfma_f32_16x16x32_bf16 v[80:83], v[164:167], v[204:207], v[80:83]
	v_mfma_f32_16x16x32_bf16 v[68:71], v[156:159], v[212:215], v[68:71]
	v_mfma_f32_16x16x32_bf16 v[64:67], v[164:167], v[212:215], v[64:67]
	v_mfma_f32_16x16x32_bf16 v[116:119], v[160:163], v[176:179], v[116:119]
	v_mfma_f32_16x16x32_bf16 v[112:115], v[168:171], v[176:179], v[112:115]
	v_mfma_f32_16x16x32_bf16 v[100:103], v[160:163], v[200:203], v[100:103]
	v_mfma_f32_16x16x32_bf16 v[96:99], v[168:171], v[200:203], v[96:99]
	v_mfma_f32_16x16x32_bf16 v[84:87], v[160:163], v[208:211], v[84:87]
	v_mfma_f32_16x16x32_bf16 v[80:83], v[168:171], v[208:211], v[80:83]
	v_mfma_f32_16x16x32_bf16 v[68:71], v[160:163], v[216:219], v[68:71]
	v_mfma_f32_16x16x32_bf16 v[64:67], v[168:171], v[216:219], v[64:67]
	s_barrier
	v_lshl_add_u64 v[136:137], s[82:83], 0, v[184:185]
	s_add_i32 s82, vcc_lo, s50
	s_mov_b32 m0, s82
	ds_read_b128 v[172:175], v142 offset:16384
	ds_read_b128 v[176:179], v142 offset:17408
	ds_read_b128 v[180:183], v142 offset:18432
	ds_read_b128 v[200:203], v142 offset:19456
	ds_read_b128 v[204:207], v142 offset:20480
	ds_read_b128 v[208:211], v142 offset:21504
	ds_read_b128 v[212:215], v142 offset:22528
	ds_read_b128 v[216:219], v142 offset:23552
	global_load_lds_dwordx4 v[136:137], off
	v_lshl_add_u64 v[220:221], v[136:137], 0, s[84:85]
	s_add_i32 m0, s82, 0x2000
	s_add_i32 s82, vcc_hi, s50
	global_load_lds_dwordx4 v[220:221], off
	v_lshl_add_u64 v[220:221], v[136:137], 0, s[86:87]
	s_mov_b32 m0, s82
	s_nop 0
	global_load_lds_dwordx4 v[220:221], off
	v_lshl_add_u64 v[220:221], v[136:137], 0, s[88:89]
	s_add_i32 m0, s82, 0x2000
	s_nop 0
	global_load_lds_dwordx4 v[220:221], off
	v_lshl_add_u64 v[220:221], s[2:3], 0, v[128:129]
	s_mov_b32 m0, s51
	v_lshl_add_u64 v[222:223], v[220:221], 0, s[84:85]
	global_load_lds_dwordx4 v[220:221], off
	s_mov_b32 m0, s66
	s_nop 0
	global_load_lds_dwordx4 v[222:223], off
	s_waitcnt vmcnt(8)
	s_waitcnt lgkmcnt(0)
	s_barrier
	s_waitcnt lgkmcnt(0)
	v_mfma_f32_16x16x32_bf16 v[60:63], v[132:135], v[172:175], v[60:63]
	v_mfma_f32_16x16x32_bf16 v[56:59], v[148:151], v[172:175], v[56:59]
	v_mfma_f32_16x16x32_bf16 v[44:47], v[132:135], v[180:183], v[44:47]
	v_mfma_f32_16x16x32_bf16 v[40:43], v[148:151], v[180:183], v[40:43]
	v_mfma_f32_16x16x32_bf16 v[28:31], v[132:135], v[204:207], v[28:31]
	v_mfma_f32_16x16x32_bf16 v[24:27], v[148:151], v[204:207], v[24:27]
	v_mfma_f32_16x16x32_bf16 v[12:15], v[132:135], v[212:215], v[12:15]
	v_mfma_f32_16x16x32_bf16 v[8:11], v[148:151], v[212:215], v[8:11]
	v_mfma_f32_16x16x32_bf16 v[60:63], v[144:147], v[176:179], v[60:63]
	v_mfma_f32_16x16x32_bf16 v[56:59], v[152:155], v[176:179], v[56:59]
	v_mfma_f32_16x16x32_bf16 v[44:47], v[144:147], v[200:203], v[44:47]
	v_mfma_f32_16x16x32_bf16 v[40:43], v[152:155], v[200:203], v[40:43]
	v_mfma_f32_16x16x32_bf16 v[28:31], v[144:147], v[208:211], v[28:31]
	v_mfma_f32_16x16x32_bf16 v[24:27], v[152:155], v[208:211], v[24:27]
	v_mfma_f32_16x16x32_bf16 v[12:15], v[144:147], v[216:219], v[12:15]
	v_mfma_f32_16x16x32_bf16 v[8:11], v[152:155], v[216:219], v[8:11]
	v_mfma_f32_16x16x32_bf16 v[52:55], v[156:159], v[172:175], v[52:55]
	v_mfma_f32_16x16x32_bf16 v[48:51], v[164:167], v[172:175], v[48:51]
	v_mfma_f32_16x16x32_bf16 v[36:39], v[156:159], v[180:183], v[36:39]
	v_mfma_f32_16x16x32_bf16 v[32:35], v[164:167], v[180:183], v[32:35]
	v_mfma_f32_16x16x32_bf16 v[20:23], v[156:159], v[204:207], v[20:23]
	v_mfma_f32_16x16x32_bf16 v[16:19], v[164:167], v[204:207], v[16:19]
	v_mfma_f32_16x16x32_bf16 v[4:7], v[156:159], v[212:215], v[4:7]
	v_mfma_f32_16x16x32_bf16 v[0:3], v[164:167], v[212:215], v[0:3]
	v_mfma_f32_16x16x32_bf16 v[52:55], v[160:163], v[176:179], v[52:55]
	v_mfma_f32_16x16x32_bf16 v[48:51], v[168:171], v[176:179], v[48:51]
	v_mfma_f32_16x16x32_bf16 v[36:39], v[160:163], v[200:203], v[36:39]
	v_mfma_f32_16x16x32_bf16 v[32:35], v[168:171], v[200:203], v[32:35]
	v_mfma_f32_16x16x32_bf16 v[20:23], v[160:163], v[208:211], v[20:23]
	v_mfma_f32_16x16x32_bf16 v[16:19], v[168:171], v[208:211], v[16:19]
	v_mfma_f32_16x16x32_bf16 v[4:7], v[160:163], v[216:219], v[4:7]
	v_mfma_f32_16x16x32_bf16 v[0:3], v[168:171], v[216:219], v[0:3]
	s_barrier
	s_add_i32 s2, 0, 0x18000
	v_add_u32_e32 v143, s2, v140
	s_add_i32 s3, 0, 0x1c000
	ds_read_b128 v[132:135], v143
	ds_read_b128 v[144:147], v143 offset:1024
	ds_read_b128 v[148:151], v143 offset:2048
	ds_read_b128 v[152:155], v143 offset:3072
	v_add_u32_e32 v143, s3, v140
	ds_read_b128 v[156:159], v143
	ds_read_b128 v[160:163], v143 offset:1024
	ds_read_b128 v[164:167], v143 offset:2048
	ds_read_b128 v[168:171], v143 offset:3072
	s_mov_b32 m0, s67
	v_lshl_add_u64 v[222:223], v[220:221], 0, s[86:87]
	ds_read_b128 v[172:175], v142 offset:32768
	ds_read_b128 v[176:179], v142 offset:33792
	ds_read_b128 v[180:183], v142 offset:34816
	ds_read_b128 v[200:203], v142 offset:35840
	ds_read_b128 v[204:207], v142 offset:36864
	ds_read_b128 v[208:211], v142 offset:37888
	ds_read_b128 v[212:215], v142 offset:38912
	ds_read_b128 v[216:219], v142 offset:39936
	global_load_lds_dwordx4 v[222:223], off
	v_lshl_add_u64 v[222:223], v[220:221], 0, s[88:89]
	s_mov_b32 m0, s76
	s_nop 0
	global_load_lds_dwordx4 v[222:223], off
	s_waitcnt vmcnt(8)
	s_waitcnt lgkmcnt(0)
	s_barrier
	s_waitcnt lgkmcnt(0)
	v_mfma_f32_16x16x32_bf16 v[124:127], v[132:135], v[172:175], v[124:127]
	v_mfma_f32_16x16x32_bf16 v[120:123], v[148:151], v[172:175], v[120:123]
	v_mfma_f32_16x16x32_bf16 v[108:111], v[132:135], v[180:183], v[108:111]
	v_mfma_f32_16x16x32_bf16 v[104:107], v[148:151], v[180:183], v[104:107]
	v_mfma_f32_16x16x32_bf16 v[92:95], v[132:135], v[204:207], v[92:95]
	v_mfma_f32_16x16x32_bf16 v[88:91], v[148:151], v[204:207], v[88:91]
	v_mfma_f32_16x16x32_bf16 v[76:79], v[132:135], v[212:215], v[76:79]
	v_mfma_f32_16x16x32_bf16 v[72:75], v[148:151], v[212:215], v[72:75]
	v_mfma_f32_16x16x32_bf16 v[124:127], v[144:147], v[176:179], v[124:127]
	v_mfma_f32_16x16x32_bf16 v[120:123], v[152:155], v[176:179], v[120:123]
	v_mfma_f32_16x16x32_bf16 v[108:111], v[144:147], v[200:203], v[108:111]
	v_mfma_f32_16x16x32_bf16 v[104:107], v[152:155], v[200:203], v[104:107]
	v_mfma_f32_16x16x32_bf16 v[92:95], v[144:147], v[208:211], v[92:95]
	v_mfma_f32_16x16x32_bf16 v[88:91], v[152:155], v[208:211], v[88:91]
	v_mfma_f32_16x16x32_bf16 v[76:79], v[144:147], v[216:219], v[76:79]
	v_mfma_f32_16x16x32_bf16 v[72:75], v[152:155], v[216:219], v[72:75]
	v_mfma_f32_16x16x32_bf16 v[116:119], v[156:159], v[172:175], v[116:119]
	v_mfma_f32_16x16x32_bf16 v[112:115], v[164:167], v[172:175], v[112:115]
	v_mfma_f32_16x16x32_bf16 v[100:103], v[156:159], v[180:183], v[100:103]
	v_mfma_f32_16x16x32_bf16 v[96:99], v[164:167], v[180:183], v[96:99]
	v_mfma_f32_16x16x32_bf16 v[84:87], v[156:159], v[204:207], v[84:87]
	v_mfma_f32_16x16x32_bf16 v[80:83], v[164:167], v[204:207], v[80:83]
	v_mfma_f32_16x16x32_bf16 v[68:71], v[156:159], v[212:215], v[68:71]
	v_mfma_f32_16x16x32_bf16 v[64:67], v[164:167], v[212:215], v[64:67]
	v_mfma_f32_16x16x32_bf16 v[116:119], v[160:163], v[176:179], v[116:119]
	v_mfma_f32_16x16x32_bf16 v[112:115], v[168:171], v[176:179], v[112:115]
	v_mfma_f32_16x16x32_bf16 v[100:103], v[160:163], v[200:203], v[100:103]
	v_mfma_f32_16x16x32_bf16 v[96:99], v[168:171], v[200:203], v[96:99]
	v_mfma_f32_16x16x32_bf16 v[84:87], v[160:163], v[208:211], v[84:87]
	v_mfma_f32_16x16x32_bf16 v[80:83], v[168:171], v[208:211], v[80:83]
	v_mfma_f32_16x16x32_bf16 v[68:71], v[160:163], v[216:219], v[68:71]
	v_mfma_f32_16x16x32_bf16 v[64:67], v[168:171], v[216:219], v[64:67]
	s_barrier
	s_add_i32 s2, s2, s50
	v_lshl_add_u64 v[222:223], v[136:137], 0, s[90:91]
	s_mov_b32 m0, s2
	ds_read_b128 v[172:175], v142 offset:49152
	ds_read_b128 v[176:179], v142 offset:50176
	ds_read_b128 v[180:183], v142 offset:51200
	ds_read_b128 v[200:203], v142 offset:52224
	ds_read_b128 v[204:207], v142 offset:53248
	ds_read_b128 v[208:211], v142 offset:54272
	ds_read_b128 v[212:215], v142 offset:55296
	ds_read_b128 v[216:219], v142 offset:56320
	global_load_lds_dwordx4 v[222:223], off
	v_lshl_add_u64 v[222:223], v[136:137], 0, s[92:93]
	s_add_i32 m0, s2, 0x2000
	s_add_i32 s2, s3, s50
	global_load_lds_dwordx4 v[222:223], off
	v_lshl_add_u64 v[222:223], v[136:137], 0, s[94:95]
	s_mov_b32 m0, s2
	v_lshl_add_u64 v[136:137], v[136:137], 0, s[96:97]
	global_load_lds_dwordx4 v[222:223], off
	s_add_i32 m0, s2, 0x2000
	s_nop 0
	global_load_lds_dwordx4 v[136:137], off
	v_lshl_add_u64 v[136:137], v[220:221], 0, s[90:91]
	s_mov_b32 m0, s77
	s_nop 0
	global_load_lds_dwordx4 v[136:137], off
	v_lshl_add_u64 v[136:137], v[220:221], 0, s[92:93]
	s_mov_b32 m0, s78
	s_nop 0
	global_load_lds_dwordx4 v[136:137], off
	s_waitcnt vmcnt(8)
	s_waitcnt lgkmcnt(0)
	s_barrier
	s_waitcnt lgkmcnt(0)
	s_cmp_lg_u32 s81, 12
	s_cbranch_scc1 .Lffn1_nossq
	v_lshl_add_u32 v248, s48, 8, v139
	v_ashrrev_i32_e32 v249, 31, v248
	v_lshl_add_u64 v[248:249], v[248:249], 2, s[16:17]
	global_load_dword v240, v[248:249], off
	global_load_dword v241, v[248:249], off offset:64
	global_load_dword v242, v[248:249], off offset:128
	global_load_dword v243, v[248:249], off offset:192
	global_load_dword v244, v[248:249], off offset:512
	global_load_dword v245, v[248:249], off offset:576
	global_load_dword v246, v[248:249], off offset:640
	global_load_dword v247, v[248:249], off offset:704
.Lffn1_nossq:
	v_mfma_f32_16x16x32_bf16 v[60:63], v[132:135], v[172:175], v[60:63]
	v_mfma_f32_16x16x32_bf16 v[56:59], v[148:151], v[172:175], v[56:59]
	v_mfma_f32_16x16x32_bf16 v[44:47], v[132:135], v[180:183], v[44:47]
	v_mfma_f32_16x16x32_bf16 v[40:43], v[148:151], v[180:183], v[40:43]
	v_mfma_f32_16x16x32_bf16 v[28:31], v[132:135], v[204:207], v[28:31]
	v_mfma_f32_16x16x32_bf16 v[24:27], v[148:151], v[204:207], v[24:27]
	v_mfma_f32_16x16x32_bf16 v[12:15], v[132:135], v[212:215], v[12:15]
	v_mfma_f32_16x16x32_bf16 v[8:11], v[148:151], v[212:215], v[8:11]
	v_mfma_f32_16x16x32_bf16 v[60:63], v[144:147], v[176:179], v[60:63]
	v_mfma_f32_16x16x32_bf16 v[56:59], v[152:155], v[176:179], v[56:59]
	v_mfma_f32_16x16x32_bf16 v[44:47], v[144:147], v[200:203], v[44:47]
	v_mfma_f32_16x16x32_bf16 v[40:43], v[152:155], v[200:203], v[40:43]
	v_mfma_f32_16x16x32_bf16 v[28:31], v[144:147], v[208:211], v[28:31]
	v_mfma_f32_16x16x32_bf16 v[24:27], v[152:155], v[208:211], v[24:27]
	v_mfma_f32_16x16x32_bf16 v[12:15], v[144:147], v[216:219], v[12:15]
	v_mfma_f32_16x16x32_bf16 v[8:11], v[152:155], v[216:219], v[8:11]
	v_mfma_f32_16x16x32_bf16 v[52:55], v[156:159], v[172:175], v[52:55]
	v_mfma_f32_16x16x32_bf16 v[48:51], v[164:167], v[172:175], v[48:51]
	v_mfma_f32_16x16x32_bf16 v[36:39], v[156:159], v[180:183], v[36:39]
	v_mfma_f32_16x16x32_bf16 v[32:35], v[164:167], v[180:183], v[32:35]
	v_mfma_f32_16x16x32_bf16 v[20:23], v[156:159], v[204:207], v[20:23]
	v_mfma_f32_16x16x32_bf16 v[16:19], v[164:167], v[204:207], v[16:19]
	v_mfma_f32_16x16x32_bf16 v[4:7], v[156:159], v[212:215], v[4:7]
	v_mfma_f32_16x16x32_bf16 v[0:3], v[164:167], v[212:215], v[0:3]
	v_mfma_f32_16x16x32_bf16 v[52:55], v[160:163], v[176:179], v[52:55]
	v_mfma_f32_16x16x32_bf16 v[48:51], v[168:171], v[176:179], v[48:51]
	v_mfma_f32_16x16x32_bf16 v[36:39], v[160:163], v[200:203], v[36:39]
	v_mfma_f32_16x16x32_bf16 v[32:35], v[168:171], v[200:203], v[32:35]
	v_mfma_f32_16x16x32_bf16 v[20:23], v[160:163], v[208:211], v[20:23]
	v_mfma_f32_16x16x32_bf16 v[16:19], v[168:171], v[208:211], v[16:19]
	v_mfma_f32_16x16x32_bf16 v[4:7], v[160:163], v[216:219], v[4:7]
	v_mfma_f32_16x16x32_bf16 v[0:3], v[168:171], v[216:219], v[0:3]
	s_barrier
	s_add_i32 s81, s81, 2
	s_add_u32 s54, s54, 0x100
	s_addc_u32 s55, s55, 0
	s_add_u32 s49, s49, 0x100
	s_addc_u32 s80, s80, 0
	s_cmp_gt_u32 s81, 13
	s_cbranch_scc0 .LBB0_1916
	s_and_b64 vcc, exec, s[18:19]
	s_cbranch_vccz .LBB0_1919
	s_barrier
.LBB0_1919:
	v_lshl_add_u32 v132, s48, 8, v139
	v_ashrrev_i32_e32 v133, 31, v132
	v_lshl_add_u64 v[134:135], v[132:133], 2, s[16:17]
	s_mov_b32 s2, 0x800000
	v_lshl_or_b32 v136, s33, 7, v141
	v_ashrrev_i32_e32 v137, 31, v136
	s_movk_i32 s3, 0x1600
	s_mov_b64 s[54:55], -1
	s_mov_b64 s[80:81], 0x1000
	s_waitcnt vmcnt(0)
	v_fmamk_f32 v133, v240, 0x3a800000, v227
	v_cmp_gt_f32_e32 vcc, s2, v133
	v_mul_f32_e32 v143, 0x4b800000, v133
	s_nop 0
	v_cndmask_b32_e32 v133, v133, v143, vcc
	v_rsq_f32_e32 v133, v133
	s_nop 0
	v_mul_f32_e32 v143, 0x45800000, v133
	v_cndmask_b32_e32 v144, v133, v143, vcc
	v_pk_mul_f32 v[124:125], v[124:125], v[144:145] op_sel_hi:[1,0]
	v_pk_mul_f32 v[116:117], v[116:117], v[144:145] op_sel_hi:[1,0]
	v_mul_f32_e32 v133, 0xbfb8aa3b, v124
	v_exp_f32_e32 v133, v133
	v_pk_mul_f32 v[118:119], v[118:119], v[144:145] op_sel_hi:[1,0]
	v_pk_mul_f32 v[120:121], v[120:121], v[144:145] op_sel_hi:[1,0]
	v_pk_mul_f32 v[112:113], v[112:113], v[144:145] op_sel_hi:[1,0]
	v_add_f32_e32 v133, 1.0, v133
	v_rcp_f32_e32 v146, v133
	v_mul_f32_e32 v133, 0xbfb8aa3b, v125
	v_exp_f32_e32 v133, v133
	v_pk_mul_f32 v[114:115], v[114:115], v[144:145] op_sel_hi:[1,0]
	v_add_f32_e32 v133, 1.0, v133
	v_rcp_f32_e32 v147, v133
	s_nop 0
	v_pk_mul_f32 v[124:125], v[124:125], v[146:147]
	s_nop 0
	v_pk_mul_f32 v[116:117], v[116:117], v[124:125]
	v_pk_mul_f32 v[124:125], v[126:127], v[144:145] op_sel_hi:[1,0]
	v_cvt_pk_bf16_f32 v116, v116, v117
	v_mul_f32_e32 v126, 0xbfb8aa3b, v124
	v_mul_f32_e32 v127, 0xbfb8aa3b, v125
	v_exp_f32_e32 v126, v126
	v_exp_f32_e32 v127, v127
	v_add_f32_e32 v126, 1.0, v126
	v_add_f32_e32 v127, 1.0, v127
	v_rcp_f32_e32 v126, v126
	v_rcp_f32_e32 v127, v127
	s_nop 0
	v_pk_mul_f32 v[124:125], v[124:125], v[126:127]
	s_nop 0
	v_pk_mul_f32 v[118:119], v[118:119], v[124:125]
	v_mul_f32_e32 v124, 0xbfb8aa3b, v120
	v_mul_f32_e32 v125, 0xbfb8aa3b, v121
	v_exp_f32_e32 v124, v124
	v_exp_f32_e32 v125, v125
	v_cvt_pk_bf16_f32 v117, v118, v119
	v_add_f32_e32 v124, 1.0, v124
	v_add_f32_e32 v125, 1.0, v125
	v_rcp_f32_e32 v124, v124
	v_rcp_f32_e32 v125, v125
	s_nop 0
	v_pk_mul_f32 v[120:121], v[120:121], v[124:125]
	s_nop 0
	v_pk_mul_f32 v[120:121], v[112:113], v[120:121]
	v_pk_mul_f32 v[112:113], v[122:123], v[144:145] op_sel_hi:[1,0]
	v_cvt_pk_bf16_f32 v118, v120, v121
	v_mul_f32_e32 v122, 0xbfb8aa3b, v112
	v_mul_f32_e32 v123, 0xbfb8aa3b, v113
	v_exp_f32_e32 v122, v122
	v_exp_f32_e32 v123, v123
	v_add_f32_e32 v122, 1.0, v122
	v_add_f32_e32 v123, 1.0, v123
	v_rcp_f32_e32 v122, v122
	v_rcp_f32_e32 v123, v123
	s_nop 0
	v_pk_mul_f32 v[112:113], v[112:113], v[122:123]
	s_nop 0
	v_pk_mul_f32 v[122:123], v[114:115], v[112:113]
	v_mov_b64_e32 v[112:113], s[10:11]
	v_mad_i64_i32 v[124:125], s[0:1], v132, s3, v[112:113]
	v_lshlrev_b64 v[114:115], 1, v[136:137]
	v_lshl_add_u64 v[124:125], v[124:125], 0, v[114:115]
	v_cvt_pk_bf16_f32 v119, v122, v123
	global_store_dwordx4 v[124:125], v[116:119], off nt
	s_nop 1
	v_or_b32_e32 v116, 16, v132
	v_ashrrev_i32_e32 v117, 31, v116
	v_lshl_add_u64 v[118:119], v[116:117], 2, s[16:17]
	v_fmamk_f32 v117, v241, 0x3a800000, v227
	v_cmp_gt_f32_e32 vcc, s2, v117
	v_mul_f32_e32 v118, 0x4b800000, v117
	s_nop 0
	v_cndmask_b32_e32 v117, v117, v118, vcc
	v_rsq_f32_e32 v117, v117
	s_nop 0
	v_mul_f32_e32 v118, 0x45800000, v117
	v_cndmask_b32_e32 v118, v117, v118, vcc
	v_pk_mul_f32 v[108:109], v[108:109], v[118:119] op_sel_hi:[1,0]
	v_pk_mul_f32 v[100:101], v[100:101], v[118:119] op_sel_hi:[1,0]
	v_mul_f32_e32 v117, 0xbfb8aa3b, v108
	v_exp_f32_e32 v117, v117
	v_pk_mul_f32 v[102:103], v[102:103], v[118:119] op_sel_hi:[1,0]
	v_pk_mul_f32 v[104:105], v[104:105], v[118:119] op_sel_hi:[1,0]
	v_pk_mul_f32 v[96:97], v[96:97], v[118:119] op_sel_hi:[1,0]
	v_add_f32_e32 v117, 1.0, v117
	v_rcp_f32_e32 v120, v117
	v_mul_f32_e32 v117, 0xbfb8aa3b, v109
	v_exp_f32_e32 v117, v117
	v_pk_mul_f32 v[98:99], v[98:99], v[118:119] op_sel_hi:[1,0]
	v_add_f32_e32 v117, 1.0, v117
	v_rcp_f32_e32 v121, v117
	s_nop 0
	v_pk_mul_f32 v[108:109], v[108:109], v[120:121]
	s_nop 0
	v_pk_mul_f32 v[100:101], v[100:101], v[108:109]
	v_pk_mul_f32 v[108:109], v[110:111], v[118:119] op_sel_hi:[1,0]
	s_nop 0
	v_mul_f32_e32 v110, 0xbfb8aa3b, v108
	v_mul_f32_e32 v111, 0xbfb8aa3b, v109
	v_exp_f32_e32 v110, v110
	v_exp_f32_e32 v111, v111
	v_add_f32_e32 v110, 1.0, v110
	v_add_f32_e32 v111, 1.0, v111
	v_rcp_f32_e32 v110, v110
	v_rcp_f32_e32 v111, v111
	s_nop 0
	v_pk_mul_f32 v[108:109], v[108:109], v[110:111]
	s_nop 0
	v_pk_mul_f32 v[102:103], v[102:103], v[108:109]
	v_mul_f32_e32 v108, 0xbfb8aa3b, v104
	v_mul_f32_e32 v109, 0xbfb8aa3b, v105
	v_exp_f32_e32 v108, v108
	v_exp_f32_e32 v109, v109
	v_add_f32_e32 v108, 1.0, v108
	v_add_f32_e32 v109, 1.0, v109
	v_rcp_f32_e32 v108, v108
	v_rcp_f32_e32 v109, v109
	s_nop 0
	v_pk_mul_f32 v[104:105], v[104:105], v[108:109]
	s_nop 0
	v_pk_mul_f32 v[104:105], v[96:97], v[104:105]
	v_pk_mul_f32 v[96:97], v[106:107], v[118:119] op_sel_hi:[1,0]
	s_nop 0
	v_mul_f32_e32 v106, 0xbfb8aa3b, v96
	v_mul_f32_e32 v107, 0xbfb8aa3b, v97
	v_exp_f32_e32 v106, v106
	v_exp_f32_e32 v107, v107
	v_add_f32_e32 v106, 1.0, v106
	v_add_f32_e32 v107, 1.0, v107
	v_rcp_f32_e32 v106, v106
	v_rcp_f32_e32 v107, v107
	s_nop 0
	v_pk_mul_f32 v[96:97], v[96:97], v[106:107]
	s_nop 0
	v_pk_mul_f32 v[106:107], v[98:99], v[96:97]
	v_mad_i64_i32 v[96:97], s[0:1], v116, s3, v[112:113]
	v_lshl_add_u64 v[108:109], v[96:97], 0, v[114:115]
	v_cvt_pk_bf16_f32 v96, v100, v101
	v_cvt_pk_bf16_f32 v97, v102, v103
	v_cvt_pk_bf16_f32 v98, v104, v105
	v_cvt_pk_bf16_f32 v99, v106, v107
	global_store_dwordx4 v[108:109], v[96:99], off nt
	s_nop 1
	v_or_b32_e32 v96, 32, v132
	v_ashrrev_i32_e32 v97, 31, v96
	v_lshl_add_u64 v[98:99], v[96:97], 2, s[16:17]
	v_fmamk_f32 v97, v242, 0x3a800000, v227
	v_cmp_gt_f32_e32 vcc, s2, v97
	v_mul_f32_e32 v98, 0x4b800000, v97
	s_nop 0
	v_cndmask_b32_e32 v97, v97, v98, vcc
	v_rsq_f32_e32 v97, v97
	s_nop 0
	v_mul_f32_e32 v98, 0x45800000, v97
	v_cndmask_b32_e32 v98, v97, v98, vcc
	v_pk_mul_f32 v[92:93], v[92:93], v[98:99] op_sel_hi:[1,0]
	v_pk_mul_f32 v[84:85], v[84:85], v[98:99] op_sel_hi:[1,0]
	v_mul_f32_e32 v97, 0xbfb8aa3b, v92
	v_exp_f32_e32 v97, v97
	v_pk_mul_f32 v[86:87], v[86:87], v[98:99] op_sel_hi:[1,0]
	v_pk_mul_f32 v[88:89], v[88:89], v[98:99] op_sel_hi:[1,0]
	v_pk_mul_f32 v[80:81], v[80:81], v[98:99] op_sel_hi:[1,0]
	v_add_f32_e32 v97, 1.0, v97
	v_rcp_f32_e32 v100, v97
	v_mul_f32_e32 v97, 0xbfb8aa3b, v93
	v_exp_f32_e32 v97, v97
	v_pk_mul_f32 v[82:83], v[82:83], v[98:99] op_sel_hi:[1,0]
	v_add_f32_e32 v97, 1.0, v97
	v_rcp_f32_e32 v101, v97
	s_nop 0
	v_pk_mul_f32 v[92:93], v[92:93], v[100:101]
	s_nop 0
	v_pk_mul_f32 v[84:85], v[84:85], v[92:93]
	v_pk_mul_f32 v[92:93], v[94:95], v[98:99] op_sel_hi:[1,0]
	s_nop 0
	v_mul_f32_e32 v94, 0xbfb8aa3b, v92
	v_mul_f32_e32 v95, 0xbfb8aa3b, v93
	v_exp_f32_e32 v94, v94
	v_exp_f32_e32 v95, v95
	v_add_f32_e32 v94, 1.0, v94
	v_add_f32_e32 v95, 1.0, v95
	v_rcp_f32_e32 v94, v94
	v_rcp_f32_e32 v95, v95
	s_nop 0
	v_pk_mul_f32 v[92:93], v[92:93], v[94:95]
	s_nop 0
	v_pk_mul_f32 v[86:87], v[86:87], v[92:93]
	v_mul_f32_e32 v92, 0xbfb8aa3b, v88
	v_mul_f32_e32 v93, 0xbfb8aa3b, v89
	v_exp_f32_e32 v92, v92
	v_exp_f32_e32 v93, v93
	v_add_f32_e32 v92, 1.0, v92
	v_add_f32_e32 v93, 1.0, v93
	v_rcp_f32_e32 v92, v92
	v_rcp_f32_e32 v93, v93
	s_nop 0
	v_pk_mul_f32 v[88:89], v[88:89], v[92:93]
	s_nop 0
	v_pk_mul_f32 v[88:89], v[80:81], v[88:89]
	v_pk_mul_f32 v[80:81], v[90:91], v[98:99] op_sel_hi:[1,0]
	s_nop 0
	v_mul_f32_e32 v90, 0xbfb8aa3b, v80
	v_mul_f32_e32 v91, 0xbfb8aa3b, v81
	v_exp_f32_e32 v90, v90
	v_exp_f32_e32 v91, v91
	v_add_f32_e32 v90, 1.0, v90
	v_add_f32_e32 v91, 1.0, v91
	v_rcp_f32_e32 v90, v90
	v_rcp_f32_e32 v91, v91
	s_nop 0
	v_pk_mul_f32 v[80:81], v[80:81], v[90:91]
	s_nop 0
	v_pk_mul_f32 v[90:91], v[82:83], v[80:81]
	v_mad_i64_i32 v[80:81], s[0:1], v96, s3, v[112:113]
	v_lshl_add_u64 v[92:93], v[80:81], 0, v[114:115]
	v_cvt_pk_bf16_f32 v80, v84, v85
	v_cvt_pk_bf16_f32 v81, v86, v87
	v_cvt_pk_bf16_f32 v82, v88, v89
	v_cvt_pk_bf16_f32 v83, v90, v91
	global_store_dwordx4 v[92:93], v[80:83], off nt
	s_nop 1
	v_or_b32_e32 v80, 48, v132
	v_ashrrev_i32_e32 v81, 31, v80
	v_lshl_add_u64 v[82:83], v[80:81], 2, s[16:17]
	v_fmamk_f32 v81, v243, 0x3a800000, v227
	v_cmp_gt_f32_e32 vcc, s2, v81
	v_mul_f32_e32 v82, 0x4b800000, v81
	s_nop 0
	v_cndmask_b32_e32 v81, v81, v82, vcc
	v_rsq_f32_e32 v81, v81
	s_nop 0
	v_mul_f32_e32 v82, 0x45800000, v81
	v_cndmask_b32_e32 v82, v81, v82, vcc
	v_pk_mul_f32 v[76:77], v[76:77], v[82:83] op_sel_hi:[1,0]
	v_pk_mul_f32 v[68:69], v[68:69], v[82:83] op_sel_hi:[1,0]
	v_mul_f32_e32 v81, 0xbfb8aa3b, v76
	v_exp_f32_e32 v81, v81
	v_pk_mul_f32 v[70:71], v[70:71], v[82:83] op_sel_hi:[1,0]
	v_pk_mul_f32 v[72:73], v[72:73], v[82:83] op_sel_hi:[1,0]
	v_pk_mul_f32 v[64:65], v[64:65], v[82:83] op_sel_hi:[1,0]
	v_add_f32_e32 v81, 1.0, v81
	v_rcp_f32_e32 v84, v81
	v_mul_f32_e32 v81, 0xbfb8aa3b, v77
	v_exp_f32_e32 v81, v81
	v_pk_mul_f32 v[66:67], v[66:67], v[82:83] op_sel_hi:[1,0]
	v_add_f32_e32 v81, 1.0, v81
	v_rcp_f32_e32 v85, v81
	s_nop 0
	v_pk_mul_f32 v[76:77], v[76:77], v[84:85]
	s_nop 0
	v_pk_mul_f32 v[68:69], v[68:69], v[76:77]
	v_pk_mul_f32 v[76:77], v[78:79], v[82:83] op_sel_hi:[1,0]
	v_cvt_pk_bf16_f32 v68, v68, v69
	v_mul_f32_e32 v78, 0xbfb8aa3b, v76
	v_mul_f32_e32 v79, 0xbfb8aa3b, v77
	v_exp_f32_e32 v78, v78
	v_exp_f32_e32 v79, v79
	v_add_f32_e32 v78, 1.0, v78
	v_add_f32_e32 v79, 1.0, v79
	v_rcp_f32_e32 v78, v78
	v_rcp_f32_e32 v79, v79
	s_nop 0
	v_pk_mul_f32 v[76:77], v[76:77], v[78:79]
	s_nop 0
	v_pk_mul_f32 v[70:71], v[70:71], v[76:77]
	v_mul_f32_e32 v76, 0xbfb8aa3b, v72
	v_mul_f32_e32 v77, 0xbfb8aa3b, v73
	v_exp_f32_e32 v76, v76
	v_exp_f32_e32 v77, v77
	v_cvt_pk_bf16_f32 v69, v70, v71
	v_add_f32_e32 v76, 1.0, v76
	v_add_f32_e32 v77, 1.0, v77
	v_rcp_f32_e32 v76, v76
	v_rcp_f32_e32 v77, v77
	s_nop 0
	v_pk_mul_f32 v[72:73], v[72:73], v[76:77]
	s_nop 0
	v_pk_mul_f32 v[64:65], v[64:65], v[72:73]
	v_pk_mul_f32 v[72:73], v[74:75], v[82:83] op_sel_hi:[1,0]
	v_cvt_pk_bf16_f32 v70, v64, v65
	v_mul_f32_e32 v74, 0xbfb8aa3b, v72
	v_mul_f32_e32 v75, 0xbfb8aa3b, v73
	v_exp_f32_e32 v74, v74
	v_exp_f32_e32 v75, v75
	v_add_u32_e32 v65, 0x80, v132
	v_add_f32_e32 v74, 1.0, v74
	v_add_f32_e32 v75, 1.0, v75
	v_rcp_f32_e32 v74, v74
	v_rcp_f32_e32 v75, v75
	s_nop 0
	v_pk_mul_f32 v[72:73], v[72:73], v[74:75]
	s_nop 0
	v_pk_mul_f32 v[66:67], v[66:67], v[72:73]
	v_mad_i64_i32 v[72:73], s[0:1], v80, s3, v[112:113]
	v_lshl_add_u64 v[72:73], v[72:73], 0, v[114:115]
	v_cvt_pk_bf16_f32 v71, v66, v67
	global_store_dwordx4 v[72:73], v[68:71], off nt
	v_fmamk_f32 v64, v244, 0x3a800000, v227
	v_cmp_gt_f32_e32 vcc, s2, v64
	v_mul_f32_e32 v66, 0x4b800000, v64
	s_nop 0
	v_cndmask_b32_e32 v64, v64, v66, vcc
	v_rsq_f32_e32 v64, v64
	s_nop 0
	v_mul_f32_e32 v66, 0x45800000, v64
	v_cndmask_b32_e32 v64, v64, v66, vcc
	v_pk_mul_f32 v[60:61], v[60:61], v[64:65] op_sel_hi:[1,0]
	v_pk_mul_f32 v[52:53], v[52:53], v[64:65] op_sel_hi:[1,0]
	v_mul_f32_e32 v66, 0xbfb8aa3b, v60
	v_mul_f32_e32 v67, 0xbfb8aa3b, v61
	v_exp_f32_e32 v66, v66
	v_exp_f32_e32 v67, v67
	v_pk_mul_f32 v[54:55], v[54:55], v[64:65] op_sel_hi:[1,0]
	v_pk_mul_f32 v[56:57], v[56:57], v[64:65] op_sel_hi:[1,0]
	v_add_f32_e32 v66, 1.0, v66
	v_add_f32_e32 v67, 1.0, v67
	v_rcp_f32_e32 v66, v66
	v_rcp_f32_e32 v67, v67
	v_pk_mul_f32 v[48:49], v[48:49], v[64:65] op_sel_hi:[1,0]
	v_pk_mul_f32 v[50:51], v[50:51], v[64:65] op_sel_hi:[1,0]
	v_pk_mul_f32 v[60:61], v[60:61], v[66:67]
	s_nop 0
	v_pk_mul_f32 v[52:53], v[52:53], v[60:61]
	v_pk_mul_f32 v[60:61], v[62:63], v[64:65] op_sel_hi:[1,0]
	v_cvt_pk_bf16_f32 v52, v52, v53
	v_mul_f32_e32 v62, 0xbfb8aa3b, v60
	v_mul_f32_e32 v63, 0xbfb8aa3b, v61
	v_exp_f32_e32 v62, v62
	v_exp_f32_e32 v63, v63
	v_add_f32_e32 v62, 1.0, v62
	v_add_f32_e32 v63, 1.0, v63
	v_rcp_f32_e32 v62, v62
	v_rcp_f32_e32 v63, v63
	s_nop 0
	v_pk_mul_f32 v[60:61], v[60:61], v[62:63]
	s_nop 0
	v_pk_mul_f32 v[54:55], v[54:55], v[60:61]
	v_mul_f32_e32 v60, 0xbfb8aa3b, v56
	v_mul_f32_e32 v61, 0xbfb8aa3b, v57
	v_exp_f32_e32 v60, v60
	v_exp_f32_e32 v61, v61
	v_cvt_pk_bf16_f32 v53, v54, v55
	v_add_f32_e32 v60, 1.0, v60
	v_add_f32_e32 v61, 1.0, v61
	v_rcp_f32_e32 v60, v60
	v_rcp_f32_e32 v61, v61
	s_nop 0
	v_pk_mul_f32 v[56:57], v[56:57], v[60:61]
	s_nop 0
	v_pk_mul_f32 v[48:49], v[48:49], v[56:57]
	v_pk_mul_f32 v[56:57], v[58:59], v[64:65] op_sel_hi:[1,0]
	v_cvt_pk_bf16_f32 v54, v48, v49
	v_mul_f32_e32 v58, 0xbfb8aa3b, v56
	v_mul_f32_e32 v59, 0xbfb8aa3b, v57
	v_exp_f32_e32 v58, v58
	v_exp_f32_e32 v59, v59
	v_add_u32_e32 v49, 0x90, v132
	v_add_f32_e32 v58, 1.0, v58
	v_add_f32_e32 v59, 1.0, v59
	v_rcp_f32_e32 v58, v58
	v_rcp_f32_e32 v59, v59
	s_nop 0
	v_pk_mul_f32 v[56:57], v[56:57], v[58:59]
	s_nop 0
	v_pk_mul_f32 v[50:51], v[50:51], v[56:57]
	v_mad_i64_i32 v[56:57], s[0:1], v65, s3, v[112:113]
	v_lshl_add_u64 v[56:57], v[56:57], 0, v[114:115]
	v_cvt_pk_bf16_f32 v55, v50, v51
	global_store_dwordx4 v[56:57], v[52:55], off nt
	v_fmamk_f32 v48, v245, 0x3a800000, v227
	v_cmp_gt_f32_e32 vcc, s2, v48
	v_mul_f32_e32 v50, 0x4b800000, v48
	s_nop 0
	v_cndmask_b32_e32 v48, v48, v50, vcc
	v_rsq_f32_e32 v48, v48
	s_nop 0
	v_mul_f32_e32 v50, 0x45800000, v48
	v_cndmask_b32_e32 v48, v48, v50, vcc
	v_pk_mul_f32 v[44:45], v[44:45], v[48:49] op_sel_hi:[1,0]
	v_pk_mul_f32 v[36:37], v[36:37], v[48:49] op_sel_hi:[1,0]
	v_mul_f32_e32 v50, 0xbfb8aa3b, v44
	v_mul_f32_e32 v51, 0xbfb8aa3b, v45
	v_exp_f32_e32 v50, v50
	v_exp_f32_e32 v51, v51
	v_pk_mul_f32 v[38:39], v[38:39], v[48:49] op_sel_hi:[1,0]
	v_pk_mul_f32 v[40:41], v[40:41], v[48:49] op_sel_hi:[1,0]
	v_add_f32_e32 v50, 1.0, v50
	v_add_f32_e32 v51, 1.0, v51
	v_rcp_f32_e32 v50, v50
	v_rcp_f32_e32 v51, v51
	v_pk_mul_f32 v[32:33], v[32:33], v[48:49] op_sel_hi:[1,0]
	v_pk_mul_f32 v[34:35], v[34:35], v[48:49] op_sel_hi:[1,0]
	v_pk_mul_f32 v[44:45], v[44:45], v[50:51]
	s_nop 0
	v_pk_mul_f32 v[36:37], v[36:37], v[44:45]
	v_pk_mul_f32 v[44:45], v[46:47], v[48:49] op_sel_hi:[1,0]
	v_cvt_pk_bf16_f32 v36, v36, v37
	v_mul_f32_e32 v46, 0xbfb8aa3b, v44
	v_mul_f32_e32 v47, 0xbfb8aa3b, v45
	v_exp_f32_e32 v46, v46
	v_exp_f32_e32 v47, v47
	v_add_f32_e32 v46, 1.0, v46
	v_add_f32_e32 v47, 1.0, v47
	v_rcp_f32_e32 v46, v46
	v_rcp_f32_e32 v47, v47
	s_nop 0
	v_pk_mul_f32 v[44:45], v[44:45], v[46:47]
	s_nop 0
	v_pk_mul_f32 v[38:39], v[38:39], v[44:45]
	v_mul_f32_e32 v44, 0xbfb8aa3b, v40
	v_mul_f32_e32 v45, 0xbfb8aa3b, v41
	v_exp_f32_e32 v44, v44
	v_exp_f32_e32 v45, v45
	v_cvt_pk_bf16_f32 v37, v38, v39
	v_add_f32_e32 v44, 1.0, v44
	v_add_f32_e32 v45, 1.0, v45
	v_rcp_f32_e32 v44, v44
	v_rcp_f32_e32 v45, v45
	s_nop 0
	v_pk_mul_f32 v[40:41], v[40:41], v[44:45]
	s_nop 0
	v_pk_mul_f32 v[32:33], v[32:33], v[40:41]
	v_pk_mul_f32 v[40:41], v[42:43], v[48:49] op_sel_hi:[1,0]
	v_cvt_pk_bf16_f32 v38, v32, v33
	v_mul_f32_e32 v42, 0xbfb8aa3b, v40
	v_mul_f32_e32 v43, 0xbfb8aa3b, v41
	v_exp_f32_e32 v42, v42
	v_exp_f32_e32 v43, v43
	v_add_u32_e32 v33, 0xa0, v132
	v_add_f32_e32 v42, 1.0, v42
	v_add_f32_e32 v43, 1.0, v43
	v_rcp_f32_e32 v42, v42
	v_rcp_f32_e32 v43, v43
	s_nop 0
	v_pk_mul_f32 v[40:41], v[40:41], v[42:43]
	s_nop 0
	v_pk_mul_f32 v[34:35], v[34:35], v[40:41]
	v_mad_i64_i32 v[40:41], s[0:1], v49, s3, v[112:113]
	v_lshl_add_u64 v[40:41], v[40:41], 0, v[114:115]
	v_cvt_pk_bf16_f32 v39, v34, v35
	global_store_dwordx4 v[40:41], v[36:39], off nt
	v_fmamk_f32 v32, v246, 0x3a800000, v227
	v_cmp_gt_f32_e32 vcc, s2, v32
	v_mul_f32_e32 v34, 0x4b800000, v32
	s_nop 0
	v_cndmask_b32_e32 v32, v32, v34, vcc
	v_rsq_f32_e32 v32, v32
	s_nop 0
	v_mul_f32_e32 v34, 0x45800000, v32
	v_cndmask_b32_e32 v32, v32, v34, vcc
	v_pk_mul_f32 v[28:29], v[28:29], v[32:33] op_sel_hi:[1,0]
	v_pk_mul_f32 v[20:21], v[20:21], v[32:33] op_sel_hi:[1,0]
	v_mul_f32_e32 v34, 0xbfb8aa3b, v28
	v_mul_f32_e32 v35, 0xbfb8aa3b, v29
	v_exp_f32_e32 v34, v34
	v_exp_f32_e32 v35, v35
	v_pk_mul_f32 v[22:23], v[22:23], v[32:33] op_sel_hi:[1,0]
	v_pk_mul_f32 v[24:25], v[24:25], v[32:33] op_sel_hi:[1,0]
	v_add_f32_e32 v34, 1.0, v34
	v_add_f32_e32 v35, 1.0, v35
	v_rcp_f32_e32 v34, v34
	v_rcp_f32_e32 v35, v35
	v_pk_mul_f32 v[16:17], v[16:17], v[32:33] op_sel_hi:[1,0]
	v_pk_mul_f32 v[18:19], v[18:19], v[32:33] op_sel_hi:[1,0]
	v_pk_mul_f32 v[28:29], v[28:29], v[34:35]
	s_nop 0
	v_pk_mul_f32 v[20:21], v[20:21], v[28:29]
	v_pk_mul_f32 v[28:29], v[30:31], v[32:33] op_sel_hi:[1,0]
	v_cvt_pk_bf16_f32 v20, v20, v21
	v_mul_f32_e32 v30, 0xbfb8aa3b, v28
	v_mul_f32_e32 v31, 0xbfb8aa3b, v29
	v_exp_f32_e32 v30, v30
	v_exp_f32_e32 v31, v31
	v_add_f32_e32 v30, 1.0, v30
	v_add_f32_e32 v31, 1.0, v31
	v_rcp_f32_e32 v30, v30
	v_rcp_f32_e32 v31, v31
	s_nop 0
	v_pk_mul_f32 v[28:29], v[28:29], v[30:31]
	s_nop 0
	v_pk_mul_f32 v[22:23], v[22:23], v[28:29]
	v_mul_f32_e32 v28, 0xbfb8aa3b, v24
	v_mul_f32_e32 v29, 0xbfb8aa3b, v25
	v_exp_f32_e32 v28, v28
	v_exp_f32_e32 v29, v29
	v_cvt_pk_bf16_f32 v21, v22, v23
	v_add_f32_e32 v28, 1.0, v28
	v_add_f32_e32 v29, 1.0, v29
	v_rcp_f32_e32 v28, v28
	v_rcp_f32_e32 v29, v29
	s_nop 0
	v_pk_mul_f32 v[24:25], v[24:25], v[28:29]
	s_nop 0
	v_pk_mul_f32 v[16:17], v[16:17], v[24:25]
	v_pk_mul_f32 v[24:25], v[26:27], v[32:33] op_sel_hi:[1,0]
	v_cvt_pk_bf16_f32 v22, v16, v17
	v_mul_f32_e32 v26, 0xbfb8aa3b, v24
	v_mul_f32_e32 v27, 0xbfb8aa3b, v25
	v_exp_f32_e32 v26, v26
	v_exp_f32_e32 v27, v27
	v_add_u32_e32 v17, 0xb0, v132
	v_add_f32_e32 v26, 1.0, v26
	v_add_f32_e32 v27, 1.0, v27
	v_rcp_f32_e32 v26, v26
	v_rcp_f32_e32 v27, v27
	s_nop 0
	v_pk_mul_f32 v[24:25], v[24:25], v[26:27]
	s_nop 0
	v_pk_mul_f32 v[18:19], v[18:19], v[24:25]
	v_mad_i64_i32 v[24:25], s[0:1], v33, s3, v[112:113]
	v_lshl_add_u64 v[24:25], v[24:25], 0, v[114:115]
	v_cvt_pk_bf16_f32 v23, v18, v19
	global_store_dwordx4 v[24:25], v[20:23], off nt
	v_fmamk_f32 v16, v247, 0x3a800000, v227
	v_cmp_gt_f32_e32 vcc, s2, v16
	v_mul_f32_e32 v18, 0x4b800000, v16
	s_nop 0
	v_cndmask_b32_e32 v16, v16, v18, vcc
	v_rsq_f32_e32 v16, v16
	s_nop 0
	v_mul_f32_e32 v18, 0x45800000, v16
	v_cndmask_b32_e32 v16, v16, v18, vcc
	v_pk_mul_f32 v[12:13], v[12:13], v[16:17] op_sel_hi:[1,0]
	v_pk_mul_f32 v[4:5], v[4:5], v[16:17] op_sel_hi:[1,0]
	v_mul_f32_e32 v18, 0xbfb8aa3b, v12
	v_mul_f32_e32 v19, 0xbfb8aa3b, v13
	v_exp_f32_e32 v18, v18
	v_exp_f32_e32 v19, v19
	v_pk_mul_f32 v[6:7], v[6:7], v[16:17] op_sel_hi:[1,0]
	v_pk_mul_f32 v[8:9], v[8:9], v[16:17] op_sel_hi:[1,0]
	v_add_f32_e32 v18, 1.0, v18
	v_add_f32_e32 v19, 1.0, v19
	v_rcp_f32_e32 v18, v18
	v_rcp_f32_e32 v19, v19
	v_pk_mul_f32 v[0:1], v[0:1], v[16:17] op_sel_hi:[1,0]
	v_pk_mul_f32 v[2:3], v[2:3], v[16:17] op_sel_hi:[1,0]
	s_andn2_b64 vcc, exec, s[6:7]
	v_pk_mul_f32 v[12:13], v[12:13], v[18:19]
	s_nop 0
	v_pk_mul_f32 v[4:5], v[4:5], v[12:13]
	v_pk_mul_f32 v[12:13], v[14:15], v[16:17] op_sel_hi:[1,0]
	s_nop 0
	v_mul_f32_e32 v14, 0xbfb8aa3b, v12
	v_mul_f32_e32 v15, 0xbfb8aa3b, v13
	v_exp_f32_e32 v14, v14
	v_exp_f32_e32 v15, v15
	v_add_f32_e32 v14, 1.0, v14
	v_add_f32_e32 v15, 1.0, v15
	v_rcp_f32_e32 v14, v14
	v_rcp_f32_e32 v15, v15
	s_nop 0
	v_pk_mul_f32 v[12:13], v[12:13], v[14:15]
	s_nop 0
	v_pk_mul_f32 v[6:7], v[6:7], v[12:13]
	v_mul_f32_e32 v12, 0xbfb8aa3b, v8
	v_mul_f32_e32 v13, 0xbfb8aa3b, v9
	v_exp_f32_e32 v12, v12
	v_exp_f32_e32 v13, v13
	v_add_f32_e32 v12, 1.0, v12
	v_add_f32_e32 v13, 1.0, v13
	v_rcp_f32_e32 v12, v12
	v_rcp_f32_e32 v13, v13
	s_nop 0
	v_pk_mul_f32 v[8:9], v[8:9], v[12:13]
	s_nop 0
	v_pk_mul_f32 v[8:9], v[0:1], v[8:9]
	v_pk_mul_f32 v[0:1], v[10:11], v[16:17] op_sel_hi:[1,0]
	s_nop 0
	v_mul_f32_e32 v10, 0xbfb8aa3b, v0
	v_mul_f32_e32 v11, 0xbfb8aa3b, v1
	v_exp_f32_e32 v10, v10
	v_exp_f32_e32 v11, v11
	v_add_f32_e32 v10, 1.0, v10
	v_add_f32_e32 v11, 1.0, v11
	v_rcp_f32_e32 v10, v10
	v_rcp_f32_e32 v11, v11
	s_nop 0
	v_pk_mul_f32 v[0:1], v[0:1], v[10:11]
	s_nop 0
	v_pk_mul_f32 v[10:11], v[2:3], v[0:1]
	v_mad_i64_i32 v[0:1], s[0:1], v17, s3, v[112:113]
	v_lshl_add_u64 v[12:13], v[0:1], 0, v[114:115]
	v_cvt_pk_bf16_f32 v0, v4, v5
	v_cvt_pk_bf16_f32 v1, v6, v7
	v_cvt_pk_bf16_f32 v2, v8, v9
	v_cvt_pk_bf16_f32 v3, v10, v11
	global_store_dwordx4 v[12:13], v[0:3], off nt
	s_cbranch_vccnz .LBB0_1912
	s_andn2_b64 vcc, exec, s[8:9]
	s_cbranch_vccnz .LBB0_1911
	s_barrier
	s_branch .LBB0_1911
